# NA unit prologue: bias table loads unrolled with a single wait instead of four serialized load+wait iterations
# baseline (speedup 1.0000x reference)
; DI void attn_na_unit(const Params& p, int li, int b, int r, int hp, char* smem) {
;     ...
;   __syncthreads();
;   for (int idx = tid; idx < 2 * 465; idx += 256) {
;     int hsel = idx >= 465 ? 1 : 0; int rem = idx - hsel * 465;
;     tab[idx] = p.ab_rpb[((size_t)(li * 8 + 2 * hp + hsel)) * 465 + rem] * LOG2E;
;   }
;   bf16x8 qf[4];
; #pragma unroll
;   for (int s = 0; s < 4; ++s) qf[s] = *(const bf16x8*)(qna + (size_t)qrow * 512 + head * 64 + s * 16 + hh * 8);
;   f32x16 O0, O1;
; #pragma unroll
;   for (int i = 0; i < 16; ++i) { O0[i] = 0.f; O1[i] = 0.f; }
;   float m = 0.f, l = 0.f;
;   const int krow = tid >> 4, kpart = tid & 15;
;   const u16* gk = kna + (size_t)(b * S_ + rs * 64 + krow) * 512 + hp * 128 + kpart * 8;
;   const u16* gv = vT + (size_t)(b * S_ + rs * 64 + krow) * 512 + hp * 128 + kpart * 8;
;   u32x4 rk[4], rv[4];
; #pragma unroll
;   for (int i = 0; i < 4; ++i) { rk[i] = *(const u32x4*)(gk + (size_t)i * 16 * 512); rv[i] = *(const u32x4*)(gv + (size_t)i * 16 * 512); }
.LBB0_1502:
	s_movk_i32 s4, 0x1d0
	v_cmp_lt_u32_e32 vcc, s4, v2
	s_movk_i32 s4, 0x744
	s_nop 0
	v_cndmask_b32_e64 v1, 0, 1, vcc
	v_or_b32_e32 v1, v1, v8
	v_cndmask_b32_e64 v11, 0, -1, vcc
	v_cndmask_b32_e32 v10, 0, v194, vcc
	v_mul_lo_u32 v144, v1, s4
	v_lshl_add_u64 v[10:11], v[2:3], 0, v[10:11]
	v_lshl_add_u64 v[12:13], s[36:37], 0, v[144:145]
	v_lshl_add_u64 v[10:11], v[10:11], 2, v[12:13]
	global_load_dword v250, v[10:11], off
	v_lshl_add_u64 v[2:3], v[2:3], 0, s[6:7]
	s_movk_i32 s4, 0x1d0
	v_cmp_lt_u32_e32 vcc, s4, v2
	s_movk_i32 s4, 0x744
	s_nop 0
	v_cndmask_b32_e64 v1, 0, 1, vcc
	v_or_b32_e32 v1, v1, v8
	v_cndmask_b32_e64 v11, 0, -1, vcc
	v_cndmask_b32_e32 v10, 0, v194, vcc
	v_mul_lo_u32 v144, v1, s4
	v_lshl_add_u64 v[10:11], v[2:3], 0, v[10:11]
	v_lshl_add_u64 v[12:13], s[36:37], 0, v[144:145]
	v_lshl_add_u64 v[10:11], v[10:11], 2, v[12:13]
	global_load_dword v251, v[10:11], off
	v_lshl_add_u64 v[2:3], v[2:3], 0, s[6:7]
	s_movk_i32 s4, 0x1d0
	v_cmp_lt_u32_e32 vcc, s4, v2
	s_movk_i32 s4, 0x744
	s_nop 0
	v_cndmask_b32_e64 v1, 0, 1, vcc
	v_or_b32_e32 v1, v1, v8
	v_cndmask_b32_e64 v11, 0, -1, vcc
	v_cndmask_b32_e32 v10, 0, v194, vcc
	v_mul_lo_u32 v144, v1, s4
	v_lshl_add_u64 v[10:11], v[2:3], 0, v[10:11]
	v_lshl_add_u64 v[12:13], s[36:37], 0, v[144:145]
	v_lshl_add_u64 v[10:11], v[10:11], 2, v[12:13]
	global_load_dword v252, v[10:11], off
	v_lshl_add_u64 v[2:3], v[2:3], 0, s[6:7]
	s_movk_i32 s4, 0x3a2
	v_cmp_gt_u32_e32 vcc, s4, v2
	s_and_saveexec_b64 s[2:3], vcc
	s_movk_i32 s4, 0x1d0
	v_cmp_lt_u32_e32 vcc, s4, v2
	s_movk_i32 s4, 0x744
	s_nop 0
	v_cndmask_b32_e64 v1, 0, 1, vcc
	v_or_b32_e32 v1, v1, v8
	v_cndmask_b32_e64 v11, 0, -1, vcc
	v_cndmask_b32_e32 v10, 0, v194, vcc
	v_mul_lo_u32 v144, v1, s4
	v_lshl_add_u64 v[10:11], v[2:3], 0, v[10:11]
	v_lshl_add_u64 v[12:13], s[36:37], 0, v[144:145]
	v_lshl_add_u64 v[10:11], v[10:11], 2, v[12:13]
	global_load_dword v253, v[10:11], off
	v_lshl_add_u64 v[2:3], v[2:3], 0, s[6:7]
	s_waitcnt vmcnt(0)
	v_mul_f32_e32 v253, 0x3fb8aa3b, v253
	ds_write_b32 v9, v253 offset:3072
	s_or_b64 exec, exec, s[2:3]
	v_mul_f32_e32 v250, 0x3fb8aa3b, v250
	v_mul_f32_e32 v251, 0x3fb8aa3b, v251
	v_mul_f32_e32 v252, 0x3fb8aa3b, v252
	ds_write_b32 v9, v250
	ds_write_b32 v9, v251 offset:1024
	ds_write_b32 v9, v252 offset:2048
	s_or_b64 exec, exec, s[2:3]
	v_readlane_b32 s2, v240, 26
	v_min_u32_e32 v2, 56, v7
	v_lshrrev_b32_e32 v49, 7, v0
	v_lshl_add_u32 v1, v36, 6, s2
	v_or_b32_e32 v112, v34, v1
	v_ashrrev_i32_e32 v113, 31, v112
	v_readlane_b32 s4, v237, 14
	v_or_b32_e32 v39, v49, v5
	v_add_u32_e32 v50, -8, v2
	v_lshlrev_b64 v[2:3], 10, v[112:113]
	v_readlane_b32 s5, v237, 15
	v_min_u32_e32 v38, 60, v6
	v_bfe_u32 v48, v35, 5, 1
	v_lshl_add_u64 v[2:3], s[4:5], 0, v[2:3]
	v_lshlrev_b32_e32 v144, 7, v39
	v_lshl_add_u64 v[2:3], v[2:3], 0, v[144:145]
	v_lshlrev_b32_e32 v32, 4, v48
	v_mov_b32_e32 v33, v145
	v_add_u32_e32 v51, -4, v38
	v_lshl_add_u64 v[2:3], v[2:3], 0, v[32:33]
	v_lshrrev_b32_e32 v33, 4, v0
	v_lshl_add_u32 v0, v51, 6, s2
	v_or_b32_e32 v144, v33, v0
	v_lshlrev_b64 v[0:1], 10, v[144:145]
	global_load_dwordx4 v[64:67], v[2:3], off
	global_load_dwordx4 v[68:71], v[2:3], off offset:32
	global_load_dwordx4 v[72:75], v[2:3], off offset:64
	global_load_dwordx4 v[76:79], v[2:3], off offset:96
	v_lshl_add_u64 v[2:3], s[28:29], 0, v[0:1]
	v_lshlrev_b32_e32 v4, 8, v4
	v_mov_b32_e32 v5, v145
	v_lshlrev_b32_e32 v6, 4, v35
	v_readlane_b32 s2, v237, 16
	v_lshl_add_u64 v[2:3], v[2:3], 0, v[4:5]
	v_and_b32_e32 v40, 0xf0, v6
	v_mov_b32_e32 v41, v145
	v_readlane_b32 s3, v237, 17
	v_lshl_add_u64 v[2:3], v[2:3], 0, v[40:41]
	v_lshlrev_b32_e32 v122, 2, v48
	v_lshl_add_u64 v[0:1], s[2:3], 0, v[0:1]
	s_movk_i32 s2, 0x4000
	v_lshl_add_u64 v[0:1], v[0:1], 0, v[4:5]
	v_add_co_u32_e32 v12, vcc, s2, v2
	v_lshl_add_u64 v[0:1], v[0:1], 0, v[40:41]
	s_nop 0
	v_addc_co_u32_e32 v13, vcc, 0, v3, vcc
	v_add_co_u32_e32 v16, vcc, s2, v0
	s_mov_b32 s2, 0x8000
	s_nop 0
	v_addc_co_u32_e32 v17, vcc, 0, v1, vcc
	v_add_co_u32_e32 v20, vcc, s2, v2
	global_load_dwordx4 v[4:7], v[2:3], off
	global_load_dwordx4 v[8:11], v[0:1], off
	v_addc_co_u32_e32 v21, vcc, 0, v3, vcc
	v_add_co_u32_e32 v24, vcc, s2, v0
	global_load_dwordx4 v[12:15], v[12:13], off
	s_nop 0
	v_addc_co_u32_e32 v25, vcc, 0, v1, vcc
	s_mov_b32 s2, 0xc000
	global_load_dwordx4 v[16:19], v[16:17], off
	v_add_co_u32_e32 v28, vcc, s2, v2
	global_load_dwordx4 v[20:23], v[20:21], off
	s_nop 0
	v_addc_co_u32_e32 v29, vcc, 0, v3, vcc
	global_load_dwordx4 v[24:27], v[24:25], off
	v_add_co_u32_e32 v42, vcc, s2, v0
	global_load_dwordx4 v[28:31], v[28:29], off
	s_nop 0
	v_addc_co_u32_e32 v43, vcc, 0, v1, vcc
	global_load_dwordx4 v[44:47], v[42:43], off
	v_add_u32_e32 v40, v117, v40
	s_movk_i32 s2, 0x110
	v_mad_u32_u24 v43, v37, s2, v117
	v_mad_u32_u24 v48, v33, s2, v40
	s_movk_i32 s2, 0x140
	s_waitcnt lgkmcnt(0)
	s_barrier
; DI f32x16 mfma32(bf16x8 a, bf16x8 b, f32x16 c) { return __builtin_amdgcn_mfma_f32_32x32x16_bf16(a, b, c, 0, 0, 0); }
; DI void attn_na_unit(const Params& p, int li, int b, int r, int hp, char* smem) {
;     ...
;   for (int kt = 0; kt < 8; ++kt) {
;     __syncthreads();
; #pragma unroll
;     for (int i = 0; i < 4; ++i) {
;       *(u32x4*)(ks + (krow + 16 * i) * KR + kpart * 16) = rk[i];
;       *(u32x4*)(vs + (krow + 16 * i) * VR + kpart * 16) = rv[i];
;     }
;     __syncthreads();
;     if (kt + 1 < 8) {
;       const int k0 = (kt + 1) * 64;
; #pragma unroll
;       for (int i = 0; i < 4; ++i) { rk[i] = *(const u32x4*)(gk + (size_t)(k0 + i * 16) * 512); rv[i] = *(const u32x4*)(gv + (size_t)(k0 + i * 16) * 512); }
;     }
;     f32x16 s0, s1;
; #pragma unroll
;     for (int i = 0; i < 16; ++i) { s0[i] = -m; s1[i] = -m; }
;     {
;       bf16x8 kf[8];
; #pragma unroll
;       for (int s = 0; s < 4; ++s) {
;         kf[2 * s] = *(const bf16x8*)(ks + r32 * KR + (hs * 64 + s * 16 + hh * 8) * 2);
;         kf[2 * s + 1] = *(const bf16x8*)(ks + (32 + r32) * KR + (hs * 64 + s * 16 + hh * 8) * 2);
;       }
;       __builtin_amdgcn_sched_barrier(0); __builtin_amdgcn_s_setprio(1);
; #pragma unroll
;       for (int s = 0; s < 4; ++s) { s0 = mfma32(kf[2 * s], qf[s], s0); s1 = mfma32(kf[2 * s + 1], qf[s], s1); }
;     __builtin_amdgcn_s_setprio(0);
; }
;     const int drow = rs + kt - r + 7;
;     const float* trow = tab + hs * 465 + drow * 31;
; #pragma unroll
;     for (int i = 0; i < 16; ++i) {
;       const int kc0 = (i & 3) + 8 * (i >> 2) + 4 * hh;
;       const int kc1 = kc0 + 32;
;       const bool v0 = (unsigned)(kc0 - cs) < 16u;
;       const bool v1 = (unsigned)(kc1 - cs) < 16u;
;       const int d0 = v0 ? (kc0 - wq + 15) : 0;
;       const int d1 = v1 ? (kc1 - wq + 15) : 0;
;       const float b0 = trow[d0], b1 = trow[d1];
;       s0[i] = v0 ? s0[i] + b0 : -1e30f;
;       s1[i] = v1 ? s1[i] + b1 : -1e30f;
;     }
	v_and_b32_e32 v42, 0x80, v35
	v_or_b32_e32 v52, v32, v42
	v_add_u32_e32 v123, v43, v52
	v_mul_u32_u24_e32 v41, 0x744, v49
	v_sub_u32_e32 v51, v51, v36
	s_waitcnt vmcnt(7)
	ds_write_b128 v48, v[4:7]
	v_mad_u32_u24 v4, v33, s2, v40
	s_mov_b32 s2, 0x10000
	s_waitcnt vmcnt(6)
	ds_write_b128 v4, v[8:11] offset:17408
	s_waitcnt vmcnt(5)
	ds_write_b128 v48, v[12:15] offset:4352
	s_waitcnt vmcnt(4)
	ds_write_b128 v4, v[16:19] offset:22528
	s_waitcnt vmcnt(3)
	ds_write_b128 v48, v[20:23] offset:8704
	s_waitcnt vmcnt(2)
	ds_write_b128 v4, v[24:27] offset:27648
	s_waitcnt vmcnt(1)
	ds_write_b128 v48, v[28:31] offset:13056
	s_waitcnt vmcnt(0)
	ds_write_b128 v4, v[44:47] offset:32768
	v_add_co_u32_e32 v4, vcc, s2, v2
	s_waitcnt lgkmcnt(0)
	s_nop 0
	v_addc_co_u32_e32 v5, vcc, 0, v3, vcc
	s_barrier
	global_load_dwordx4 v[80:83], v[4:5], off
	v_add_co_u32_e32 v4, vcc, s2, v0
	s_mov_b32 s2, 0x14000
	s_nop 0
	v_addc_co_u32_e32 v5, vcc, 0, v1, vcc
	global_load_dwordx4 v[84:87], v[4:5], off
	v_add_co_u32_e32 v4, vcc, s2, v2
	s_nop 1
	v_addc_co_u32_e32 v5, vcc, 0, v3, vcc
	global_load_dwordx4 v[88:91], v[4:5], off
	v_add_co_u32_e32 v4, vcc, s2, v0
	s_mov_b32 s2, 0x18000
	s_nop 0
	v_addc_co_u32_e32 v5, vcc, 0, v1, vcc
	global_load_dwordx4 v[92:95], v[4:5], off
	v_add_co_u32_e32 v4, vcc, s2, v2
	s_nop 1
	v_addc_co_u32_e32 v5, vcc, 0, v3, vcc
	global_load_dwordx4 v[96:99], v[4:5], off
	v_add_co_u32_e32 v4, vcc, s2, v0
	s_mov_b32 s2, 0x1c000
	s_nop 0
	v_addc_co_u32_e32 v5, vcc, 0, v1, vcc
	v_add_co_u32_e32 v2, vcc, s2, v2
	global_load_dwordx4 v[100:103], v[4:5], off
	s_nop 0
	v_addc_co_u32_e32 v3, vcc, 0, v3, vcc
	v_add_co_u32_e32 v0, vcc, s2, v0
	global_load_dwordx4 v[104:107], v[2:3], off
	s_nop 0
	v_addc_co_u32_e32 v1, vcc, 0, v1, vcc
	global_load_dwordx4 v[108:111], v[0:1], off
	ds_read_b128 v[44:47], v123 offset:8704
	ds_read_b128 v[52:55], v123
	ds_read_b128 v[56:59], v123 offset:32
	ds_read_b128 v[60:63], v123 offset:8736
	ds_read_b128 v[124:127], v123 offset:64
	ds_read_b128 v[128:131], v123 offset:8768
	ds_read_b128 v[132:135], v123 offset:96
	ds_read_b128 v[136:139], v123 offset:8800
	s_setprio 1
	s_mov_b32 s9, s8
	s_mov_b32 s10, s8
	s_mov_b32 s11, s8
	s_mov_b32 s12, s8
	s_mov_b32 s13, s8
	s_mov_b32 s14, s8
	s_mov_b32 s15, s8
	s_mov_b32 s16, s8
	s_mov_b32 s17, s8
	s_mov_b32 s18, s8
	s_mov_b32 s19, s8
	s_mov_b32 s20, s8
	s_mov_b32 s21, s8
	s_mov_b32 s22, s8
	s_mov_b32 s23, s8
	v_mov_b64_e32 v[0:1], s[8:9]
	v_mov_b64_e32 v[2:3], s[10:11]
	v_mov_b64_e32 v[4:5], s[12:13]
	v_mov_b64_e32 v[6:7], s[14:15]
	v_mov_b64_e32 v[8:9], s[16:17]
	v_mov_b64_e32 v[10:11], s[18:19]
	v_mov_b64_e32 v[12:13], s[20:21]
	v_mov_b64_e32 v[14:15], s[22:23]
	s_waitcnt lgkmcnt(6)
	s_nop 0
	v_mfma_f32_32x32x16_bf16 v[16:31], v[52:55], v[64:67], v[0:15]
	v_mfma_f32_32x32x16_bf16 v[0:15], v[44:47], v[64:67], v[0:15]
	s_waitcnt lgkmcnt(5)
	v_mfma_f32_32x32x16_bf16 v[16:31], v[56:59], v[68:71], v[16:31]
	s_waitcnt lgkmcnt(4)
	v_mfma_f32_32x32x16_bf16 v[0:15], v[60:63], v[68:71], v[0:15]
	s_waitcnt lgkmcnt(3)
	v_mfma_f32_32x32x16_bf16 v[16:31], v[124:127], v[72:75], v[16:31]
	s_waitcnt lgkmcnt(2)
	v_mfma_f32_32x32x16_bf16 v[0:15], v[128:131], v[72:75], v[0:15]
	s_waitcnt lgkmcnt(1)
	v_mfma_f32_32x32x16_bf16 v[16:31], v[132:135], v[76:79], v[16:31]
	s_waitcnt lgkmcnt(0)
	v_mfma_f32_32x32x16_bf16 v[0:15], v[136:139], v[76:79], v[0:15]
	s_setprio 0
	s_movk_i32 s2, 0x7c
	v_mul_lo_u32 v43, v51, s2
	v_add3_u32 v63, v117, v41, v43
	v_or_b32_e32 v43, 32, v122
	v_sub_u32_e32 v44, v122, v50
	v_cmp_gt_u32_e64 s[76:77], 16, v44
	v_sub_u32_e32 v44, v43, v50
	v_sub_u32_e32 v43, v43, v34
	v_add_u32_e32 v43, 15, v43
	v_cmp_gt_u32_e64 s[78:79], 16, v44
	v_mov_b32_e32 v60, 0xf149f2ca
	v_mov_b32_e32 v61, 0xf149f2ca
	v_cndmask_b32_e64 v43, 0, v43, s[78:79]
	v_lshl_add_u32 v44, v43, 2, v63
	ds_read_b32 v62, v44 offset:38756
	v_sub_u32_e32 v44, v122, v34
	v_lshl_add_u32 v114, v44, 2, v63
	s_and_saveexec_b64 s[2:3], s[76:77]
	s_cbranch_execz .LBB0_1505
	ds_read_b32 v44, v114 offset:38816
	s_waitcnt lgkmcnt(0)
	v_add_f32_e32 v61, v16, v44
